# attention LSTOREX: wait only for the register staging set being stored (vmcnt(5)); the other set's loads stay in flight across the tile (2-tile lookahead as the source intends)
# baseline (speedup 1.0000x reference)
; __device__ __forceinline__ void attn_unit(const Params& p, int b, int h, int q0, int nkeys, char* smem) {
;     ...
;     uint4 ak0, ak1, ak2, av0, av1, bk0, bk1, bk2, bv0, bv1;
;     const int vdv = tid >> 3, vcc = tid & 7;
.LBB0_462:
	s_setprio 1
	ds_read_b128 v[160:163], v104 offset:0
	ds_read_b128 v[164:167], v104 offset:3328
	ds_read_b128 v[168:171], v104 offset:6656
	ds_read_b128 v[172:175], v104 offset:9984
	ds_read_b128 v[224:227], v104 offset:64
	ds_read_b128 v[228:231], v104 offset:3392
	ds_read_b128 v[232:235], v104 offset:6720
	ds_read_b128 v[236:239], v104 offset:10048
	s_waitcnt lgkmcnt(6)
	v_mfma_f32_16x16x32_bf16 v[124:127], v[160:163], v[0:3], -4.0
	v_mfma_f32_16x16x32_bf16 v[128:131], v[160:163], v[12:15], -4.0
	ds_read_b128 v[160:163], v104 offset:128
	v_mfma_f32_16x16x32_bf16 v[132:135], v[164:167], v[0:3], -4.0
	v_mfma_f32_16x16x32_bf16 v[136:139], v[164:167], v[12:15], -4.0
	ds_read_b128 v[164:167], v104 offset:3456
	s_waitcnt lgkmcnt(6)
	v_mfma_f32_16x16x32_bf16 v[140:143], v[168:171], v[0:3], -4.0
	v_mfma_f32_16x16x32_bf16 v[144:147], v[168:171], v[12:15], -4.0
	ds_read_b128 v[168:171], v104 offset:6784
	v_mfma_f32_16x16x32_bf16 v[148:151], v[172:175], v[0:3], -4.0
	v_mfma_f32_16x16x32_bf16 v[152:155], v[172:175], v[12:15], -4.0
	ds_read_b128 v[172:175], v104 offset:10112
	s_waitcnt lgkmcnt(6)
	v_mfma_f32_16x16x32_bf16 v[124:127], v[224:227], v[4:7], v[124:127]
	v_mfma_f32_16x16x32_bf16 v[128:131], v[224:227], v[16:19], v[128:131]
	ds_read_b64 v[224:225], v219 offset:13312
	ds_read_b64 v[226:227], v219 offset:13344
	v_mfma_f32_16x16x32_bf16 v[132:135], v[228:231], v[4:7], v[132:135]
	v_mfma_f32_16x16x32_bf16 v[136:139], v[228:231], v[16:19], v[136:139]
	ds_read_b64 v[228:229], v219 offset:15616
	ds_read_b64 v[230:231], v219 offset:15648
	s_waitcnt lgkmcnt(8)
	v_mfma_f32_16x16x32_bf16 v[140:143], v[232:235], v[4:7], v[140:143]
	v_mfma_f32_16x16x32_bf16 v[144:147], v[232:235], v[16:19], v[144:147]
	ds_read_b64 v[232:233], v219 offset:17920
	ds_read_b64 v[234:235], v219 offset:17952
	v_mfma_f32_16x16x32_bf16 v[148:151], v[236:239], v[4:7], v[148:151]
	v_mfma_f32_16x16x32_bf16 v[152:155], v[236:239], v[16:19], v[152:155]
	ds_read_b64 v[236:237], v219 offset:20224
	ds_read_b64 v[238:239], v219 offset:20256
	s_waitcnt lgkmcnt(10)
	v_mfma_f32_16x16x32_bf16 v[124:127], v[160:163], v[8:11], v[124:127]
	v_mfma_f32_16x16x32_bf16 v[128:131], v[160:163], v[20:23], v[128:131]
	ds_read_b64 v[160:161], v219 offset:13376
	ds_read_b64 v[162:163], v219 offset:13408
	v_mfma_f32_16x16x32_bf16 v[132:135], v[164:167], v[8:11], v[132:135]
	v_mfma_f32_16x16x32_bf16 v[136:139], v[164:167], v[20:23], v[136:139]
	ds_read_b64 v[164:165], v219 offset:15680
	ds_read_b64 v[166:167], v219 offset:15712
	s_waitcnt lgkmcnt(12)
	v_mfma_f32_16x16x32_bf16 v[140:143], v[168:171], v[8:11], v[140:143]
	v_mfma_f32_16x16x32_bf16 v[144:147], v[168:171], v[20:23], v[144:147]
	ds_read_b64 v[168:169], v219 offset:17984
	ds_read_b64 v[170:171], v219 offset:18016
	v_mfma_f32_16x16x32_bf16 v[148:151], v[172:175], v[8:11], v[148:151]
	v_mfma_f32_16x16x32_bf16 v[152:155], v[172:175], v[20:23], v[152:155]
	ds_read_b64 v[172:173], v219 offset:20288
	ds_read_b64 v[174:175], v219 offset:20320
	s_setprio 0
	v_exp_f32_e32 v124, v124
	v_exp_f32_e32 v125, v125
	v_exp_f32_e32 v126, v126
	v_exp_f32_e32 v127, v127
	v_add_f32_e32 v118, v118, v124
	v_add_f32_e32 v119, v119, v125
	v_exp_f32_e32 v128, v128
	v_exp_f32_e32 v129, v129
	v_add_f32_e32 v118, v118, v126
	v_add_f32_e32 v119, v119, v127
	v_exp_f32_e32 v130, v130
	v_exp_f32_e32 v131, v131
	v_add_f32_e32 v176, v176, v128
	v_add_f32_e32 v177, v177, v129
	v_exp_f32_e32 v132, v132
	v_exp_f32_e32 v133, v133
	v_add_f32_e32 v176, v176, v130
	v_add_f32_e32 v177, v177, v131
	v_exp_f32_e32 v134, v134
	v_exp_f32_e32 v135, v135
	v_add_f32_e32 v118, v118, v132
	v_add_f32_e32 v119, v119, v133
	v_exp_f32_e32 v136, v136
	v_exp_f32_e32 v137, v137
	v_add_f32_e32 v118, v118, v134
	v_add_f32_e32 v119, v119, v135
	v_exp_f32_e32 v138, v138
	v_exp_f32_e32 v139, v139
	v_add_f32_e32 v176, v176, v136
	v_add_f32_e32 v177, v177, v137
	v_cvt_pk_bf16_f32 v240, v124, v125
	v_add_f32_e32 v176, v176, v138
	v_add_f32_e32 v177, v177, v139
	v_cvt_pk_bf16_f32 v241, v126, v127
	v_cvt_pk_bf16_f32 v242, v132, v133
	v_cvt_pk_bf16_f32 v243, v134, v135
	v_cvt_pk_bf16_f32 v244, v128, v129
	v_cvt_pk_bf16_f32 v245, v130, v131
	v_cvt_pk_bf16_f32 v246, v136, v137
	v_cvt_pk_bf16_f32 v247, v138, v139
	s_waitcnt lgkmcnt(12)
	v_mfma_f32_16x16x32_bf16 v[92:95], v[224:227], v[240:243], v[92:95]
	v_exp_f32_e32 v140, v140
	v_exp_f32_e32 v141, v141
	v_exp_f32_e32 v142, v142
	v_exp_f32_e32 v143, v143
	v_add_f32_e32 v118, v118, v140
	v_mfma_f32_16x16x32_bf16 v[84:87], v[224:227], v[244:247], v[84:87]
	v_add_f32_e32 v119, v119, v141
	v_exp_f32_e32 v144, v144
	v_exp_f32_e32 v145, v145
	v_add_f32_e32 v118, v118, v142
	v_add_f32_e32 v119, v119, v143
	v_mfma_f32_16x16x32_bf16 v[88:91], v[228:231], v[240:243], v[88:91]
	v_exp_f32_e32 v146, v146
	v_exp_f32_e32 v147, v147
	v_add_f32_e32 v176, v176, v144
	v_add_f32_e32 v177, v177, v145
	v_exp_f32_e32 v148, v148
	v_mfma_f32_16x16x32_bf16 v[76:79], v[228:231], v[244:247], v[76:79]
	v_exp_f32_e32 v149, v149
	v_add_f32_e32 v176, v176, v146
	v_add_f32_e32 v177, v177, v147
	v_exp_f32_e32 v150, v150
	v_exp_f32_e32 v151, v151
	s_waitcnt lgkmcnt(8)
	v_mfma_f32_16x16x32_bf16 v[80:83], v[232:235], v[240:243], v[80:83]
	v_add_f32_e32 v118, v118, v148
	v_add_f32_e32 v119, v119, v149
	v_exp_f32_e32 v152, v152
	v_exp_f32_e32 v153, v153
	v_add_f32_e32 v118, v118, v150
	v_mfma_f32_16x16x32_bf16 v[68:71], v[232:235], v[244:247], v[68:71]
	v_add_f32_e32 v119, v119, v151
	v_exp_f32_e32 v154, v154
	v_exp_f32_e32 v155, v155
	v_add_f32_e32 v176, v176, v152
	v_add_f32_e32 v177, v177, v153
	v_mfma_f32_16x16x32_bf16 v[72:75], v[236:239], v[240:243], v[72:75]
	v_cvt_pk_bf16_f32 v96, v140, v141
	v_add_f32_e32 v176, v176, v154
	v_add_f32_e32 v177, v177, v155
	v_cvt_pk_bf16_f32 v97, v142, v143
	v_cvt_pk_bf16_f32 v98, v148, v149
	v_mfma_f32_16x16x32_bf16 v[64:67], v[236:239], v[244:247], v[64:67]
	v_cvt_pk_bf16_f32 v99, v150, v151
	v_cvt_pk_bf16_f32 v100, v144, v145
	v_cvt_pk_bf16_f32 v101, v146, v147
	v_cvt_pk_bf16_f32 v102, v152, v153
	v_cvt_pk_bf16_f32 v103, v154, v155
	s_nop 1
	s_waitcnt lgkmcnt(4)
	v_mfma_f32_16x16x32_bf16 v[92:95], v[160:163], v[96:99], v[92:95]
	v_mfma_f32_16x16x32_bf16 v[84:87], v[160:163], v[100:103], v[84:87]
	v_mfma_f32_16x16x32_bf16 v[88:91], v[164:167], v[96:99], v[88:91]
	v_mfma_f32_16x16x32_bf16 v[76:79], v[164:167], v[100:103], v[76:79]
	s_waitcnt lgkmcnt(0)
	v_mfma_f32_16x16x32_bf16 v[80:83], v[168:171], v[96:99], v[80:83]
	v_mfma_f32_16x16x32_bf16 v[68:71], v[168:171], v[100:103], v[68:71]
	v_mfma_f32_16x16x32_bf16 v[72:75], v[172:175], v[96:99], v[72:75]
	v_mfma_f32_16x16x32_bf16 v[64:67], v[172:175], v[100:103], v[64:67]
	s_add_i32 s44, s42, -2
	s_cmp_ge_u32 s44, s35
	s_cbranch_scc1 .LBB0_464
	s_cmp_lt_u32 s43, s35
	s_cbranch_scc1 .Llsa_5
	s_waitcnt vmcnt(0)
	s_branch .Llsa_go
.Llsa_5:
	s_waitcnt vmcnt(5)
.Llsa_go:
	ds_write_b128 v115, v[24:27] offset:22528
	ds_write_b128 v117, v[28:31] offset:22528
	ds_write_b128 v217, v[36:39] offset:22528
	ds_write_b128 v218, v[32:35] offset:35840
	ds_write_b128 v218, v[40:43] offset:40448

; __device__ __forceinline__ void attn_unit(const Params& p, int b, int h, int q0, int nkeys, char* smem) {
;     ...
;     uint4 ak0, ak1, ak2, av0, av1, bk0, bk1, bk2, bv0, bv1;
;     const int vdv = tid >> 3, vcc = tid & 7;
.LBB0_466:
	s_setprio 1
	ds_read_b128 v[160:163], v104 offset:22528
	ds_read_b128 v[164:167], v104 offset:25856
	ds_read_b128 v[168:171], v104 offset:29184
	ds_read_b128 v[172:175], v104 offset:32512
	ds_read_b128 v[224:227], v104 offset:22592
	ds_read_b128 v[228:231], v104 offset:25920
	ds_read_b128 v[232:235], v104 offset:29248
	ds_read_b128 v[236:239], v104 offset:32576
	s_waitcnt lgkmcnt(6)
	v_mfma_f32_16x16x32_bf16 v[124:127], v[160:163], v[0:3], -4.0
	v_mfma_f32_16x16x32_bf16 v[128:131], v[160:163], v[12:15], -4.0
	ds_read_b128 v[160:163], v104 offset:22656
	v_mfma_f32_16x16x32_bf16 v[132:135], v[164:167], v[0:3], -4.0
	v_mfma_f32_16x16x32_bf16 v[136:139], v[164:167], v[12:15], -4.0
	ds_read_b128 v[164:167], v104 offset:25984
	s_waitcnt lgkmcnt(6)
	v_mfma_f32_16x16x32_bf16 v[140:143], v[168:171], v[0:3], -4.0
	v_mfma_f32_16x16x32_bf16 v[144:147], v[168:171], v[12:15], -4.0
	ds_read_b128 v[168:171], v104 offset:29312
	v_mfma_f32_16x16x32_bf16 v[148:151], v[172:175], v[0:3], -4.0
	v_mfma_f32_16x16x32_bf16 v[152:155], v[172:175], v[12:15], -4.0
	ds_read_b128 v[172:175], v104 offset:32640
	s_waitcnt lgkmcnt(6)
	v_mfma_f32_16x16x32_bf16 v[124:127], v[224:227], v[4:7], v[124:127]
	v_mfma_f32_16x16x32_bf16 v[128:131], v[224:227], v[16:19], v[128:131]
	ds_read_b64 v[224:225], v219 offset:35840
	ds_read_b64 v[226:227], v219 offset:35872
	v_mfma_f32_16x16x32_bf16 v[132:135], v[228:231], v[4:7], v[132:135]
	v_mfma_f32_16x16x32_bf16 v[136:139], v[228:231], v[16:19], v[136:139]
	ds_read_b64 v[228:229], v219 offset:38144
	ds_read_b64 v[230:231], v219 offset:38176
	s_waitcnt lgkmcnt(8)
	v_mfma_f32_16x16x32_bf16 v[140:143], v[232:235], v[4:7], v[140:143]
	v_mfma_f32_16x16x32_bf16 v[144:147], v[232:235], v[16:19], v[144:147]
	ds_read_b64 v[232:233], v219 offset:40448
	ds_read_b64 v[234:235], v219 offset:40480
	v_mfma_f32_16x16x32_bf16 v[148:151], v[236:239], v[4:7], v[148:151]
	v_mfma_f32_16x16x32_bf16 v[152:155], v[236:239], v[16:19], v[152:155]
	ds_read_b64 v[236:237], v219 offset:42752
	ds_read_b64 v[238:239], v219 offset:42784
	s_waitcnt lgkmcnt(10)
	v_mfma_f32_16x16x32_bf16 v[124:127], v[160:163], v[8:11], v[124:127]
	v_mfma_f32_16x16x32_bf16 v[128:131], v[160:163], v[20:23], v[128:131]
	ds_read_b64 v[160:161], v219 offset:35904
	ds_read_b64 v[162:163], v219 offset:35936
	v_mfma_f32_16x16x32_bf16 v[132:135], v[164:167], v[8:11], v[132:135]
	v_mfma_f32_16x16x32_bf16 v[136:139], v[164:167], v[20:23], v[136:139]
	ds_read_b64 v[164:165], v219 offset:38208
	ds_read_b64 v[166:167], v219 offset:38240
	s_waitcnt lgkmcnt(12)
	v_mfma_f32_16x16x32_bf16 v[140:143], v[168:171], v[8:11], v[140:143]
	v_mfma_f32_16x16x32_bf16 v[144:147], v[168:171], v[20:23], v[144:147]
	ds_read_b64 v[168:169], v219 offset:40512
	ds_read_b64 v[170:171], v219 offset:40544
	v_mfma_f32_16x16x32_bf16 v[148:151], v[172:175], v[8:11], v[148:151]
	v_mfma_f32_16x16x32_bf16 v[152:155], v[172:175], v[20:23], v[152:155]
	ds_read_b64 v[172:173], v219 offset:42816
	ds_read_b64 v[174:175], v219 offset:42848
	s_setprio 0
	v_exp_f32_e32 v124, v124
	v_exp_f32_e32 v125, v125
	v_exp_f32_e32 v126, v126
	v_exp_f32_e32 v127, v127
	v_add_f32_e32 v118, v118, v124
	v_add_f32_e32 v119, v119, v125
	v_exp_f32_e32 v128, v128
	v_exp_f32_e32 v129, v129
	v_add_f32_e32 v118, v118, v126
	v_add_f32_e32 v119, v119, v127
	v_exp_f32_e32 v130, v130
	v_exp_f32_e32 v131, v131
	v_add_f32_e32 v176, v176, v128
	v_add_f32_e32 v177, v177, v129
	v_exp_f32_e32 v132, v132
	v_exp_f32_e32 v133, v133
	v_add_f32_e32 v176, v176, v130
	v_add_f32_e32 v177, v177, v131
	v_exp_f32_e32 v134, v134
	v_exp_f32_e32 v135, v135
	v_add_f32_e32 v118, v118, v132
	v_add_f32_e32 v119, v119, v133
	v_exp_f32_e32 v136, v136
	v_exp_f32_e32 v137, v137
	v_add_f32_e32 v118, v118, v134
	v_add_f32_e32 v119, v119, v135
	v_exp_f32_e32 v138, v138
	v_exp_f32_e32 v139, v139
	v_add_f32_e32 v176, v176, v136
	v_add_f32_e32 v177, v177, v137
	v_cvt_pk_bf16_f32 v240, v124, v125
	v_add_f32_e32 v176, v176, v138
	v_add_f32_e32 v177, v177, v139
	v_cvt_pk_bf16_f32 v241, v126, v127
	v_cvt_pk_bf16_f32 v242, v132, v133
	v_cvt_pk_bf16_f32 v243, v134, v135
	v_cvt_pk_bf16_f32 v244, v128, v129
	v_cvt_pk_bf16_f32 v245, v130, v131
	v_cvt_pk_bf16_f32 v246, v136, v137
	v_cvt_pk_bf16_f32 v247, v138, v139
	s_waitcnt lgkmcnt(12)
	v_mfma_f32_16x16x32_bf16 v[92:95], v[224:227], v[240:243], v[92:95]
	v_exp_f32_e32 v140, v140
	v_exp_f32_e32 v141, v141
	v_exp_f32_e32 v142, v142
	v_exp_f32_e32 v143, v143
	v_add_f32_e32 v118, v118, v140
	v_mfma_f32_16x16x32_bf16 v[84:87], v[224:227], v[244:247], v[84:87]
	v_add_f32_e32 v119, v119, v141
	v_exp_f32_e32 v144, v144
	v_exp_f32_e32 v145, v145
	v_add_f32_e32 v118, v118, v142
	v_add_f32_e32 v119, v119, v143
	v_mfma_f32_16x16x32_bf16 v[88:91], v[228:231], v[240:243], v[88:91]
	v_exp_f32_e32 v146, v146
	v_exp_f32_e32 v147, v147
	v_add_f32_e32 v176, v176, v144
	v_add_f32_e32 v177, v177, v145
	v_exp_f32_e32 v148, v148
	v_mfma_f32_16x16x32_bf16 v[76:79], v[228:231], v[244:247], v[76:79]
	v_exp_f32_e32 v149, v149
	v_add_f32_e32 v176, v176, v146
	v_add_f32_e32 v177, v177, v147
	v_exp_f32_e32 v150, v150
	v_exp_f32_e32 v151, v151
	s_waitcnt lgkmcnt(8)
	v_mfma_f32_16x16x32_bf16 v[80:83], v[232:235], v[240:243], v[80:83]
	v_add_f32_e32 v118, v118, v148
	v_add_f32_e32 v119, v119, v149
	v_exp_f32_e32 v152, v152
	v_exp_f32_e32 v153, v153
	v_add_f32_e32 v118, v118, v150
	v_mfma_f32_16x16x32_bf16 v[68:71], v[232:235], v[244:247], v[68:71]
	v_add_f32_e32 v119, v119, v151
	v_exp_f32_e32 v154, v154
	v_exp_f32_e32 v155, v155
	v_add_f32_e32 v176, v176, v152
	v_add_f32_e32 v177, v177, v153
	v_mfma_f32_16x16x32_bf16 v[72:75], v[236:239], v[240:243], v[72:75]
	v_cvt_pk_bf16_f32 v96, v140, v141
	v_add_f32_e32 v176, v176, v154
	v_add_f32_e32 v177, v177, v155
	v_cvt_pk_bf16_f32 v97, v142, v143
	v_cvt_pk_bf16_f32 v98, v148, v149
	v_mfma_f32_16x16x32_bf16 v[64:67], v[236:239], v[244:247], v[64:67]
	v_cvt_pk_bf16_f32 v99, v150, v151
	v_cvt_pk_bf16_f32 v100, v144, v145
	v_cvt_pk_bf16_f32 v101, v146, v147
	v_cvt_pk_bf16_f32 v102, v152, v153
	v_cvt_pk_bf16_f32 v103, v154, v155
	s_nop 1
	s_waitcnt lgkmcnt(4)
	v_mfma_f32_16x16x32_bf16 v[92:95], v[160:163], v[96:99], v[92:95]
	v_mfma_f32_16x16x32_bf16 v[84:87], v[160:163], v[100:103], v[84:87]
	v_mfma_f32_16x16x32_bf16 v[88:91], v[164:167], v[96:99], v[88:91]
	v_mfma_f32_16x16x32_bf16 v[76:79], v[164:167], v[100:103], v[76:79]
	s_waitcnt lgkmcnt(0)
	v_mfma_f32_16x16x32_bf16 v[80:83], v[168:171], v[96:99], v[80:83]
	v_mfma_f32_16x16x32_bf16 v[68:71], v[168:171], v[100:103], v[68:71]
	v_mfma_f32_16x16x32_bf16 v[72:75], v[172:175], v[96:99], v[72:75]
	v_mfma_f32_16x16x32_bf16 v[64:67], v[172:175], v[100:103], v[64:67]
	s_andn2_b64 vcc, exec, s[0:1]
	s_cbranch_vccnz .LBB0_459
	s_cmp_lt_u32 s42, s35
	s_cbranch_scc1 .Llsb_5
	s_waitcnt vmcnt(0)
	s_branch .Llsb_go

.Llsb_go:
	ds_write_b128 v115, v[44:47]
	ds_write_b128 v117, v[48:51]
	ds_write_b128 v217, v[52:55]
	ds_write_b128 v218, v[56:59] offset:13312
	ds_write_b128 v218, v[60:63] offset:17920
	s_branch .LBB0_459
